# phase 0 weight-tile loop: the loop-top wait no longer includes the previous tile's store (vmcnt(1) when a store was issued)
# speedup vs baseline: 1.0084x; 1.0084x over previous
.LBB0_415:
	s_mov_b32 s45, 0
	s_mov_b32 s8, s70
	s_waitcnt vmcnt(0)
	v_mov_b32_e32 v2, v160
	s_load_dwordx2 s[10:11], s[0:1], 0x100
	s_ashr_i32 s9, s8, 31
	s_lshl_b64 s[6:7], s[8:9], 9
	v_ashrrev_i32_e32 v3, 31, v2
	v_lshl_add_u64 v[50:51], s[6:7], 0, v[2:3]
	v_cmp_gt_u64_e32 vcc, s[98:99], v[50:51]
	s_waitcnt lgkmcnt(0)
	s_and_saveexec_b64 s[12:13], vcc
	s_cbranch_execz .LBB0_430
	s_lshl_b64 s[16:17], s[8:9], 13
	s_lshl_b64 s[8:9], s[8:9], 14
	v_lshlrev_b64 v[4:5], 5, v[2:3]
	v_lshl_add_u64 v[36:37], s[8:9], 0, v[4:5]
	s_add_u32 s8, s82, s6
	s_addc_u32 s9, s83, s7
	v_lshl_add_u64 v[4:5], s[8:9], 0, v[2:3]
	s_add_u32 s8, s66, s6
	s_addc_u32 s9, s67, s7
	s_load_dwordx2 s[14:15], s[0:1], 0x0
	s_add_u32 s6, s68, s6
	s_addc_u32 s7, s69, s7
	v_lshl_add_u64 v[34:35], v[2:3], 4, s[16:17]
	v_lshlrev_b64 v[38:39], 5, v[4:5]
	v_lshlrev_b64 v[40:41], 4, v[4:5]
	v_lshl_add_u64 v[4:5], s[8:9], 0, v[2:3]
	v_lshl_add_u64 v[2:3], s[6:7], 0, v[2:3]
	v_lshlrev_b64 v[46:47], 4, v[2:3]
	v_lshlrev_b64 v[48:49], 5, v[2:3]
	v_mov_b32_e32 v2, 0
	v_lshlrev_b64 v[42:43], 5, v[4:5]
	v_lshlrev_b64 v[44:45], 4, v[4:5]
	s_mov_b64 s[16:17], 0
	s_mov_b64 s[18:19], s[10:11]
	v_mov_b32_e32 v3, v2
	v_mov_b32_e32 v4, v2
	v_mov_b32_e32 v5, v2
	v_mov_b32_e32 v6, v2
	v_mov_b32_e32 v7, v2
	v_mov_b32_e32 v8, v2
	v_mov_b32_e32 v9, v2
	v_mov_b32_e32 v14, v2
	v_mov_b32_e32 v15, v2
	v_mov_b32_e32 v16, v2
	v_mov_b32_e32 v17, v2
	v_mov_b32_e32 v10, v2
	v_mov_b32_e32 v11, v2
	v_mov_b32_e32 v12, v2
	v_mov_b32_e32 v13, v2
	v_mov_b32_e32 v18, v2
	v_mov_b32_e32 v19, v2
	v_mov_b32_e32 v20, v2
	v_mov_b32_e32 v21, v2
	v_mov_b32_e32 v22, v2
	v_mov_b32_e32 v23, v2
	v_mov_b32_e32 v24, v2
	v_mov_b32_e32 v25, v2
	s_branch .LBB0_418

.LBB0_457:
	s_mul_i32 s8, s18, 0x2400
	s_cmp_eq_u32 s45, 0
	s_cbranch_scc1 .Lp0_w0
	s_waitcnt vmcnt(1)
	s_branch .Lp0_w1

.Lp0_w1:
	s_mov_b32 s45, 0
	v_pk_mul_f32 v[18:19], v[2:3], v[12:13] op_sel_hi:[1,0]
	s_add_i32 s22, s8, 0
	v_pk_mul_f32 v[14:15], v[4:5], v[12:13] op_sel_hi:[1,0]
	v_cvt_pk_bf16_f32 v17, v18, s0
	v_lshlrev_b32_e32 v18, 1, v11
	s_mul_i32 s8, s10, 48
	s_mul_hi_u32 s9, s14, 48
	v_add3_u32 v18, s22, v16, v18
	v_cvt_pk_bf16_f32 v14, v14, s0
	s_add_i32 s15, s9, s8
	v_pk_mul_f32 v[22:23], v[6:7], v[12:13] op_sel_hi:[1,0]
	ds_write_b16 v18, v14 offset:288
	v_cvt_pk_bf16_f32 v14, v15, s0
	s_mul_i32 s14, s14, 48
	s_getpc_b64 s[12:13]
	s_add_u32 s12, s12, g_segs@rel32@lo+20
	s_addc_u32 s13, s13, g_segs@rel32@hi+28
	ds_write_b16 v18, v14 offset:432
	v_cvt_pk_bf16_f32 v14, v22, s0
	s_add_u32 s8, s12, s14
	v_pk_mul_f32 v[20:21], v[8:9], v[12:13] op_sel_hi:[1,0]
	ds_write_b16 v18, v14 offset:576
	v_cvt_pk_bf16_f32 v14, v23, s0
	s_addc_u32 s9, s13, s15
	ds_write_b16 v18, v17
	v_cvt_pk_bf16_f32 v17, v19, s0
	ds_write_b16 v18, v14 offset:720
	v_cvt_pk_bf16_f32 v14, v20, s0
	s_getpc_b64 s[10:11]
	s_add_u32 s10, s10, g_segs@rel32@lo+28
	s_addc_u32 s11, s11, g_segs@rel32@hi+36
	ds_write_b16 v18, v17 offset:144
	ds_write_b16 v18, v14 offset:864
	s_add_u32 s14, s10, s14
	s_addc_u32 s15, s11, s15
	s_load_dword s23, s[8:9], 0x0
	s_nop 0
	s_load_dwordx4 s[8:11], s[14:15], 0x0
	v_cvt_pk_bf16_f32 v14, v21, s0
	s_andn2_b64 vcc, exec, s[6:7]
	ds_write_b16 v18, v14 offset:1008
	s_cbranch_vccnz .LBB0_467
	s_mul_i32 s25, s19, 48
	s_getpc_b64 s[6:7]
	s_add_u32 s6, s6, g_segs@rel32@lo+4
	s_addc_u32 s7, s7, g_segs@rel32@hi+12
	s_mul_hi_i32 s24, s19, 48
	s_add_u32 s14, s6, s25
	s_addc_u32 s15, s7, s24
	s_add_u32 s6, s12, s25
	s_addc_u32 s7, s13, s24
	s_load_dword s26, s[6:7], 0x0
	s_getpc_b64 s[6:7]
	s_add_u32 s6, s6, g_segs@rel32@lo+44
	s_addc_u32 s7, s7, g_segs@rel32@hi+52
	s_add_u32 s6, s6, s25
	s_addc_u32 s7, s7, s24
	s_abs_i32 s24, s20
	s_waitcnt lgkmcnt(0)
	s_add_i32 s12, s26, 63
	s_ashr_i32 s12, s12, 6
	s_abs_i32 s13, s12
	v_cvt_f32_u32_e32 v2, s13
	s_sub_i32 s27, 0, s13
	s_xor_b32 s25, s20, s12
	s_ashr_i32 s25, s25, 31
	v_rcp_iflag_f32_e32 v2, v2
	s_load_dwordx2 s[6:7], s[6:7], 0x0
	v_mov_b32_e32 v12, 1.0
	v_mov_b32_e32 v5, 0
	v_mul_f32_e32 v2, 0x4f7ffffe, v2
	v_cvt_u32_f32_e32 v2, v2
	v_mov_b32_e32 v4, 0
	v_mov_b32_e32 v3, 0
	v_mov_b32_e32 v9, 0
	v_readfirstlane_b32 s28, v2
	s_mul_i32 s27, s27, s28
	s_mul_hi_u32 s27, s28, s27
	s_add_i32 s28, s28, s27
	s_mul_hi_u32 s27, s24, s28
	s_mul_i32 s28, s27, s13
	s_sub_i32 s24, s24, s28
	s_add_i32 s29, s27, 1
	s_sub_i32 s28, s24, s13
	s_cmp_ge_u32 s24, s13
	s_cselect_b32 s27, s29, s27
	s_cselect_b32 s24, s28, s24
	s_add_i32 s28, s27, 1
	s_cmp_ge_u32 s24, s13
	s_cselect_b32 s13, s28, s27
	s_xor_b32 s13, s13, s25
	s_sub_i32 s24, s13, s25
	s_mul_i32 s12, s24, s12
	s_sub_i32 s12, s20, s12
	v_lshl_or_b32 v14, s12, 6, v10
	s_waitcnt lgkmcnt(0)
	s_cmp_lg_u32 s6, 3
	s_cselect_b64 s[12:13], -1, 0
	v_cmp_gt_i32_e32 vcc, s26, v14
	s_and_b64 s[26:27], s[12:13], vcc
	v_mov_b32_e32 v2, 0
	v_mov_b32_e32 v8, 0
	v_mov_b32_e32 v7, 0
	v_mov_b32_e32 v6, 0
	s_and_saveexec_b64 s[12:13], s[26:27]
	s_cbranch_execz .LBB0_466
	s_load_dwordx4 s[28:31], s[14:15], 0x0
	v_lshl_add_u32 v17, s24, 6, v11
	v_ashrrev_i32_e32 v15, 31, v14
	s_waitcnt lgkmcnt(0)
	s_ashr_i32 s15, s28, 31
	s_mov_b32 s14, s28
	s_lshl_b64 s[14:15], s[14:15], 3
	s_add_u32 s14, s0, s14
	s_addc_u32 s15, s1, s15
	s_load_dwordx2 s[14:15], s[14:15], 0x0
	s_mov_b32 s24, s29
	s_ashr_i32 s25, s29, 31
	s_lshl_b64 s[24:25], s[24:25], 2
	v_mad_i64_i32 v[2:3], s[26:27], s30, v17, 0
	s_waitcnt lgkmcnt(0)
	s_add_u32 s14, s14, s24
	s_addc_u32 s15, s15, s25
	s_ashr_i32 s25, s31, 31
	v_lshl_add_u64 v[2:3], v[2:3], 2, s[14:15]
	s_mov_b32 s24, s31
	v_lshl_add_u64 v[2:3], s[24:25], 2, v[2:3]
	v_lshl_add_u64 v[2:3], v[14:15], 2, v[2:3]
	global_load_dwordx4 v[6:9], v[2:3], off offset:16
	s_nop 0
	global_load_dwordx4 v[2:5], v[2:3], off
	s_cmp_lt_i32 s6, 2
	s_mov_b64 s[14:15], -1
	s_cbranch_scc1 .LBB0_463
	s_cmp_eq_u32 s6, 2
	v_mov_b32_e32 v12, 1.0
	s_cbranch_scc0 .LBB0_462
	s_load_dwordx2 s[14:15], s[0:1], 0x70
	v_add_u32_e32 v14, s7, v17
	v_ashrrev_i32_e32 v15, 31, v14
	s_waitcnt lgkmcnt(0)
	v_lshl_add_u64 v[14:15], v[14:15], 2, s[14:15]
	global_load_dword v12, v[14:15], off

.LBB0_467:
	s_waitcnt lgkmcnt(0)
	s_add_i32 s6, s23, 63
	s_ashr_i32 s6, s6, 6
	s_abs_i32 s7, s6
	v_cvt_f32_u32_e32 v14, s7
	s_sub_i32 s14, 0, s7
	s_abs_i32 s12, s2
	s_xor_b32 s13, s2, s6
	v_rcp_iflag_f32_e32 v14, v14
	s_ashr_i32 s13, s13, 31
	s_barrier
	v_mul_f32_e32 v14, 0x4f7ffffe, v14
	v_cvt_u32_f32_e32 v14, v14
	s_nop 0
	v_readfirstlane_b32 s15, v14
	s_mul_i32 s14, s14, s15
	s_mul_hi_u32 s14, s15, s14
	s_add_i32 s15, s15, s14
	s_mul_hi_u32 s14, s12, s15
	s_mul_i32 s15, s14, s7
	s_sub_i32 s12, s12, s15
	s_add_i32 s24, s14, 1
	s_sub_i32 s15, s12, s7
	s_cmp_ge_u32 s12, s7
	s_cselect_b32 s14, s24, s14
	s_cselect_b32 s12, s15, s12
	s_add_i32 s15, s14, 1
	s_cmp_ge_u32 s12, s7
	s_cselect_b32 s7, s15, s14
	s_xor_b32 s7, s7, s13
	s_sub_i32 s12, s7, s13
	s_mul_i32 s6, s12, s6
	s_sub_i32 s2, s2, s6
	v_lshl_add_u32 v14, s2, 6, v11
	v_cmp_gt_i32_e32 vcc, s23, v14
	s_and_saveexec_b64 s[6:7], vcc
	s_cbranch_execz .LBB0_448
	v_lshlrev_b32_e32 v15, 1, v10
	s_ashr_i32 s2, s8, 31
	v_add3_u32 v15, s22, v13, v15
	s_add_u32 s14, s16, s8
	v_add_u32_e32 v14, s11, v14
	ds_read_b128 v[18:21], v15
	s_addc_u32 s15, s17, s2
	v_mad_i64_i32 v[14:15], s[8:9], v14, s9, 0
	v_lshl_add_u64 v[14:15], v[14:15], 1, s[14:15]
	s_ashr_i32 s11, s10, 31
	s_lshl_b32 s8, s12, 6
	v_lshl_add_u64 v[14:15], s[10:11], 1, v[14:15]
	s_ashr_i32 s9, s8, 31
	v_lshl_add_u64 v[14:15], s[8:9], 1, v[14:15]
	v_lshl_add_u64 v[14:15], v[14:15], 0, v[0:1]
	s_waitcnt lgkmcnt(0)
	global_store_dwordx4 v[14:15], v[18:21], off
	s_mov_b32 s45, 1
	s_branch .LBB0_448
